# GEMM K-loops: removed the redundant s_waitcnt lgkmcnt(0) at the head of each MFMA block (the pre-barrier lgkmcnt(0) already drained; 12 sites)
# speedup vs baseline: 1.0107x; 1.0050x over previous
.LBB0_50:
	s_add_u32 s8, s58, 0xfffc0080
	s_addc_u32 s9, s59, -1
	s_add_i32 s10, 0, 0x10000
	s_cmp_eq_u32 s85, 12
	s_cselect_b32 s41, s53, s9
	s_cselect_b32 s40, s69, s8
	s_cselect_b32 s29, s51, s84
	s_cselect_b32 s28, s72, s73
	s_add_i32 s11, 0, 0x14000
	v_add_u32_e32 v158, s10, v150
	v_add_u32_e32 v174, s11, v150
	ds_read_b128 v[142:145], v158
	ds_read_b128 v[146:149], v158 offset:1024
	ds_read_b128 v[154:157], v158 offset:2048
	ds_read_b128 v[158:161], v158 offset:3072
	ds_read_b128 v[162:165], v174
	ds_read_b128 v[166:169], v174 offset:1024
	ds_read_b128 v[170:173], v174 offset:2048
	ds_read_b128 v[174:177], v174 offset:3072
	v_lshl_add_u64 v[210:211], s[58:59], 0, v[138:139]
	s_add_i32 m0, s61, 0xc000
	ds_read_b128 v[178:181], v153
	ds_read_b128 v[182:185], v153 offset:1024
	ds_read_b128 v[186:189], v153 offset:2048
	ds_read_b128 v[190:193], v153 offset:3072
	ds_read_b128 v[194:197], v153 offset:4096
	ds_read_b128 v[198:201], v153 offset:5120
	ds_read_b128 v[202:205], v153 offset:6144
	ds_read_b128 v[206:209], v153 offset:7168
	global_load_lds_dwordx4 v[210:211], off
	v_lshl_add_u64 v[210:211], s[58:59], 0, v[140:141]
	s_add_i32 m0, s61, 0xe000
	s_nop 0
	global_load_lds_dwordx4 v[210:211], off
	s_waitcnt vmcnt(8)
	s_waitcnt lgkmcnt(0)
	s_barrier
	s_setprio 1
	v_mfma_f32_16x16x32_bf16 v[126:129], v[142:145], v[178:181], v[126:129]
	v_mfma_f32_16x16x32_bf16 v[118:121], v[154:157], v[178:181], v[118:121]
	v_mfma_f32_16x16x32_bf16 v[110:113], v[142:145], v[186:189], v[110:113]
	v_mfma_f32_16x16x32_bf16 v[102:105], v[154:157], v[186:189], v[102:105]
	v_mfma_f32_16x16x32_bf16 v[94:97], v[142:145], v[194:197], v[94:97]
	v_mfma_f32_16x16x32_bf16 v[86:89], v[154:157], v[194:197], v[86:89]
	v_mfma_f32_16x16x32_bf16 v[78:81], v[142:145], v[202:205], v[78:81]
	v_mfma_f32_16x16x32_bf16 v[70:73], v[154:157], v[202:205], v[70:73]
	v_mfma_f32_16x16x32_bf16 v[126:129], v[146:149], v[182:185], v[126:129]
	v_mfma_f32_16x16x32_bf16 v[118:121], v[158:161], v[182:185], v[118:121]
	v_mfma_f32_16x16x32_bf16 v[110:113], v[146:149], v[190:193], v[110:113]
	v_mfma_f32_16x16x32_bf16 v[102:105], v[158:161], v[190:193], v[102:105]
	v_mfma_f32_16x16x32_bf16 v[94:97], v[146:149], v[198:201], v[94:97]
	v_mfma_f32_16x16x32_bf16 v[86:89], v[158:161], v[198:201], v[86:89]
	v_mfma_f32_16x16x32_bf16 v[78:81], v[146:149], v[206:209], v[78:81]
	v_mfma_f32_16x16x32_bf16 v[70:73], v[158:161], v[206:209], v[70:73]
	v_mfma_f32_16x16x32_bf16 v[122:125], v[162:165], v[178:181], v[122:125]
	v_mfma_f32_16x16x32_bf16 v[114:117], v[170:173], v[178:181], v[114:117]
	v_mfma_f32_16x16x32_bf16 v[106:109], v[162:165], v[186:189], v[106:109]
	v_mfma_f32_16x16x32_bf16 v[98:101], v[170:173], v[186:189], v[98:101]
	v_mfma_f32_16x16x32_bf16 v[90:93], v[162:165], v[194:197], v[90:93]
	v_mfma_f32_16x16x32_bf16 v[82:85], v[170:173], v[194:197], v[82:85]
	v_mfma_f32_16x16x32_bf16 v[74:77], v[162:165], v[202:205], v[74:77]
	v_mfma_f32_16x16x32_bf16 v[66:69], v[170:173], v[202:205], v[66:69]
	v_mfma_f32_16x16x32_bf16 v[122:125], v[166:169], v[182:185], v[122:125]
	v_mfma_f32_16x16x32_bf16 v[114:117], v[174:177], v[182:185], v[114:117]
	v_mfma_f32_16x16x32_bf16 v[106:109], v[166:169], v[190:193], v[106:109]
	v_mfma_f32_16x16x32_bf16 v[98:101], v[174:177], v[190:193], v[98:101]
	v_mfma_f32_16x16x32_bf16 v[90:93], v[166:169], v[198:201], v[90:93]
	v_mfma_f32_16x16x32_bf16 v[82:85], v[174:177], v[198:201], v[82:85]
	v_mfma_f32_16x16x32_bf16 v[74:77], v[166:169], v[206:209], v[74:77]
	v_mfma_f32_16x16x32_bf16 v[66:69], v[174:177], v[206:209], v[66:69]
	s_setprio 0
	s_barrier
	s_add_i32 s8, s10, s31
	v_lshl_add_u64 v[210:211], s[28:29], 0, v[130:131]
	s_mov_b32 m0, s8
	ds_read_b128 v[178:181], v153 offset:16384
	ds_read_b128 v[182:185], v153 offset:17408
	ds_read_b128 v[186:189], v153 offset:18432
	ds_read_b128 v[190:193], v153 offset:19456
	ds_read_b128 v[194:197], v153 offset:20480
	ds_read_b128 v[198:201], v153 offset:21504
	ds_read_b128 v[202:205], v153 offset:22528
	ds_read_b128 v[206:209], v153 offset:23552
	global_load_lds_dwordx4 v[210:211], off
	s_add_i32 m0, s8, 0x2000
	s_add_u32 s8, s28, 0x40000
	v_lshl_add_u64 v[212:213], s[28:29], 0, v[132:133]
	s_addc_u32 s9, s29, 0
	s_add_i32 s10, s11, s31
	global_load_lds_dwordx4 v[212:213], off
	v_lshl_add_u64 v[214:215], s[8:9], 0, v[130:131]
	s_mov_b32 m0, s10
	v_lshl_add_u64 v[216:217], s[40:41], 0, v[134:135]
	global_load_lds_dwordx4 v[214:215], off
	v_lshl_add_u64 v[214:215], s[8:9], 0, v[132:133]
	s_add_i32 m0, s10, 0x2000
	s_nop 0
	global_load_lds_dwordx4 v[214:215], off
	v_lshl_add_u64 v[214:215], s[40:41], 0, v[136:137]
	s_mov_b32 m0, s61
	s_nop 0
	global_load_lds_dwordx4 v[214:215], off
	s_mov_b32 m0, s62
	s_nop 0
	global_load_lds_dwordx4 v[216:217], off
	s_waitcnt vmcnt(8)
	s_waitcnt lgkmcnt(0)
	s_barrier
	s_setprio 1
	v_mfma_f32_16x16x32_bf16 v[62:65], v[142:145], v[178:181], v[62:65]
	v_mfma_f32_16x16x32_bf16 v[54:57], v[154:157], v[178:181], v[54:57]
	v_mfma_f32_16x16x32_bf16 v[46:49], v[142:145], v[186:189], v[46:49]
	v_mfma_f32_16x16x32_bf16 v[38:41], v[154:157], v[186:189], v[38:41]
	v_mfma_f32_16x16x32_bf16 v[30:33], v[142:145], v[194:197], v[30:33]
	v_mfma_f32_16x16x32_bf16 v[22:25], v[154:157], v[194:197], v[22:25]
	v_mfma_f32_16x16x32_bf16 v[14:17], v[142:145], v[202:205], v[14:17]
	v_mfma_f32_16x16x32_bf16 v[6:9], v[154:157], v[202:205], v[6:9]
	v_mfma_f32_16x16x32_bf16 v[62:65], v[146:149], v[182:185], v[62:65]
	v_mfma_f32_16x16x32_bf16 v[54:57], v[158:161], v[182:185], v[54:57]
	v_mfma_f32_16x16x32_bf16 v[46:49], v[146:149], v[190:193], v[46:49]
	v_mfma_f32_16x16x32_bf16 v[38:41], v[158:161], v[190:193], v[38:41]
	v_mfma_f32_16x16x32_bf16 v[30:33], v[146:149], v[198:201], v[30:33]
	v_mfma_f32_16x16x32_bf16 v[22:25], v[158:161], v[198:201], v[22:25]
	v_mfma_f32_16x16x32_bf16 v[14:17], v[146:149], v[206:209], v[14:17]
	v_mfma_f32_16x16x32_bf16 v[6:9], v[158:161], v[206:209], v[6:9]
	v_mfma_f32_16x16x32_bf16 v[58:61], v[162:165], v[178:181], v[58:61]
	v_mfma_f32_16x16x32_bf16 v[50:53], v[170:173], v[178:181], v[50:53]
	v_mfma_f32_16x16x32_bf16 v[42:45], v[162:165], v[186:189], v[42:45]
	v_mfma_f32_16x16x32_bf16 v[34:37], v[170:173], v[186:189], v[34:37]
	v_mfma_f32_16x16x32_bf16 v[26:29], v[162:165], v[194:197], v[26:29]
	v_mfma_f32_16x16x32_bf16 v[18:21], v[170:173], v[194:197], v[18:21]
	v_mfma_f32_16x16x32_bf16 v[10:13], v[162:165], v[202:205], v[10:13]
	v_mfma_f32_16x16x32_bf16 v[2:5], v[170:173], v[202:205], v[2:5]
	v_mfma_f32_16x16x32_bf16 v[58:61], v[166:169], v[182:185], v[58:61]
	v_mfma_f32_16x16x32_bf16 v[50:53], v[174:177], v[182:185], v[50:53]
	v_mfma_f32_16x16x32_bf16 v[42:45], v[166:169], v[190:193], v[42:45]
	v_mfma_f32_16x16x32_bf16 v[34:37], v[174:177], v[190:193], v[34:37]
	v_mfma_f32_16x16x32_bf16 v[26:29], v[166:169], v[198:201], v[26:29]
	v_mfma_f32_16x16x32_bf16 v[18:21], v[174:177], v[198:201], v[18:21]
	v_mfma_f32_16x16x32_bf16 v[10:13], v[166:169], v[206:209], v[10:13]
	v_mfma_f32_16x16x32_bf16 v[2:5], v[174:177], v[206:209], v[2:5]
	s_setprio 0
	s_barrier
	s_add_i32 s10, 0, 0x18000
	s_add_i32 s11, 0, 0x1c000
	v_add_u32_e32 v158, s10, v150
	v_add_u32_e32 v174, s11, v150
	ds_read_b128 v[142:145], v158
	ds_read_b128 v[146:149], v158 offset:1024
	ds_read_b128 v[154:157], v158 offset:2048
	ds_read_b128 v[158:161], v158 offset:3072
	ds_read_b128 v[162:165], v174
	ds_read_b128 v[166:169], v174 offset:1024
	ds_read_b128 v[170:173], v174 offset:2048
	ds_read_b128 v[174:177], v174 offset:3072
	s_add_u32 s8, s40, 0x40000
	s_addc_u32 s9, s41, 0
	s_mov_b32 m0, s63
	v_lshl_add_u64 v[218:219], s[8:9], 0, v[136:137]
	ds_read_b128 v[178:181], v153 offset:32768
	ds_read_b128 v[182:185], v153 offset:33792
	ds_read_b128 v[186:189], v153 offset:34816
	ds_read_b128 v[190:193], v153 offset:35840
	ds_read_b128 v[194:197], v153 offset:36864
	ds_read_b128 v[198:201], v153 offset:37888
	ds_read_b128 v[202:205], v153 offset:38912
	ds_read_b128 v[206:209], v153 offset:39936
	global_load_lds_dwordx4 v[218:219], off
	v_lshl_add_u64 v[218:219], s[8:9], 0, v[134:135]
	s_mov_b32 m0, s64
	s_nop 0
	global_load_lds_dwordx4 v[218:219], off
	s_waitcnt vmcnt(8)
	s_waitcnt lgkmcnt(0)
	s_barrier
	s_setprio 1
	v_mfma_f32_16x16x32_bf16 v[126:129], v[142:145], v[178:181], v[126:129]
	v_mfma_f32_16x16x32_bf16 v[118:121], v[154:157], v[178:181], v[118:121]
	v_mfma_f32_16x16x32_bf16 v[110:113], v[142:145], v[186:189], v[110:113]
	v_mfma_f32_16x16x32_bf16 v[102:105], v[154:157], v[186:189], v[102:105]
	v_mfma_f32_16x16x32_bf16 v[94:97], v[142:145], v[194:197], v[94:97]
	v_mfma_f32_16x16x32_bf16 v[86:89], v[154:157], v[194:197], v[86:89]
	v_mfma_f32_16x16x32_bf16 v[78:81], v[142:145], v[202:205], v[78:81]
	v_mfma_f32_16x16x32_bf16 v[70:73], v[154:157], v[202:205], v[70:73]
	v_mfma_f32_16x16x32_bf16 v[126:129], v[146:149], v[182:185], v[126:129]
	v_mfma_f32_16x16x32_bf16 v[118:121], v[158:161], v[182:185], v[118:121]
	v_mfma_f32_16x16x32_bf16 v[110:113], v[146:149], v[190:193], v[110:113]
	v_mfma_f32_16x16x32_bf16 v[102:105], v[158:161], v[190:193], v[102:105]
	v_mfma_f32_16x16x32_bf16 v[94:97], v[146:149], v[198:201], v[94:97]
	v_mfma_f32_16x16x32_bf16 v[86:89], v[158:161], v[198:201], v[86:89]
	v_mfma_f32_16x16x32_bf16 v[78:81], v[146:149], v[206:209], v[78:81]
	v_mfma_f32_16x16x32_bf16 v[70:73], v[158:161], v[206:209], v[70:73]
	v_mfma_f32_16x16x32_bf16 v[122:125], v[162:165], v[178:181], v[122:125]
	v_mfma_f32_16x16x32_bf16 v[114:117], v[170:173], v[178:181], v[114:117]
	v_mfma_f32_16x16x32_bf16 v[106:109], v[162:165], v[186:189], v[106:109]
	v_mfma_f32_16x16x32_bf16 v[98:101], v[170:173], v[186:189], v[98:101]
	v_mfma_f32_16x16x32_bf16 v[90:93], v[162:165], v[194:197], v[90:93]
	v_mfma_f32_16x16x32_bf16 v[82:85], v[170:173], v[194:197], v[82:85]
	v_mfma_f32_16x16x32_bf16 v[74:77], v[162:165], v[202:205], v[74:77]
	v_mfma_f32_16x16x32_bf16 v[66:69], v[170:173], v[202:205], v[66:69]
	v_mfma_f32_16x16x32_bf16 v[122:125], v[166:169], v[182:185], v[122:125]
	v_mfma_f32_16x16x32_bf16 v[114:117], v[174:177], v[182:185], v[114:117]
	v_mfma_f32_16x16x32_bf16 v[106:109], v[166:169], v[190:193], v[106:109]
	v_mfma_f32_16x16x32_bf16 v[98:101], v[174:177], v[190:193], v[98:101]
	v_mfma_f32_16x16x32_bf16 v[90:93], v[166:169], v[198:201], v[90:93]
	v_mfma_f32_16x16x32_bf16 v[82:85], v[174:177], v[198:201], v[82:85]
	v_mfma_f32_16x16x32_bf16 v[74:77], v[166:169], v[206:209], v[74:77]
	v_mfma_f32_16x16x32_bf16 v[66:69], v[174:177], v[206:209], v[66:69]
	s_setprio 0
	s_barrier
	s_add_i32 s8, s10, s31
	v_lshl_add_u64 v[210:211], v[210:211], 0, s[82:83]
	s_mov_b32 m0, s8
	ds_read_b128 v[178:181], v153 offset:49152
	ds_read_b128 v[182:185], v153 offset:50176
	ds_read_b128 v[186:189], v153 offset:51200
	ds_read_b128 v[190:193], v153 offset:52224
	ds_read_b128 v[194:197], v153 offset:53248
	ds_read_b128 v[198:201], v153 offset:54272
	ds_read_b128 v[202:205], v153 offset:55296
	ds_read_b128 v[206:209], v153 offset:56320
	global_load_lds_dwordx4 v[210:211], off
	s_add_i32 m0, s8, 0x2000
	s_add_u32 s8, s28, 0x40080
	v_lshl_add_u64 v[210:211], v[212:213], 0, s[82:83]
	s_addc_u32 s9, s29, 0
	s_add_i32 s10, s11, s31
	global_load_lds_dwordx4 v[210:211], off
	v_lshl_add_u64 v[210:211], s[8:9], 0, v[130:131]
	s_mov_b32 m0, s10
	s_nop 0
	global_load_lds_dwordx4 v[210:211], off
	v_lshl_add_u64 v[210:211], s[8:9], 0, v[132:133]
	s_add_i32 m0, s10, 0x2000
	s_nop 0
	global_load_lds_dwordx4 v[210:211], off
	v_lshl_add_u64 v[210:211], v[214:215], 0, s[82:83]
	s_mov_b32 m0, s65
	s_nop 0
	global_load_lds_dwordx4 v[210:211], off
	v_lshl_add_u64 v[210:211], v[216:217], 0, s[82:83]
	s_mov_b32 m0, s66
	s_nop 0
	global_load_lds_dwordx4 v[210:211], off
	s_waitcnt vmcnt(8)
	s_waitcnt lgkmcnt(0)
	s_barrier
	s_setprio 1
	v_mfma_f32_16x16x32_bf16 v[62:65], v[142:145], v[178:181], v[62:65]
	v_mfma_f32_16x16x32_bf16 v[54:57], v[154:157], v[178:181], v[54:57]
	v_mfma_f32_16x16x32_bf16 v[46:49], v[142:145], v[186:189], v[46:49]
	v_mfma_f32_16x16x32_bf16 v[38:41], v[154:157], v[186:189], v[38:41]
	v_mfma_f32_16x16x32_bf16 v[30:33], v[142:145], v[194:197], v[30:33]
	v_mfma_f32_16x16x32_bf16 v[22:25], v[154:157], v[194:197], v[22:25]
	v_mfma_f32_16x16x32_bf16 v[14:17], v[142:145], v[202:205], v[14:17]
	v_mfma_f32_16x16x32_bf16 v[6:9], v[154:157], v[202:205], v[6:9]
	v_mfma_f32_16x16x32_bf16 v[62:65], v[146:149], v[182:185], v[62:65]
	v_mfma_f32_16x16x32_bf16 v[54:57], v[158:161], v[182:185], v[54:57]
	v_mfma_f32_16x16x32_bf16 v[46:49], v[146:149], v[190:193], v[46:49]
	v_mfma_f32_16x16x32_bf16 v[38:41], v[158:161], v[190:193], v[38:41]
	v_mfma_f32_16x16x32_bf16 v[30:33], v[146:149], v[198:201], v[30:33]
	v_mfma_f32_16x16x32_bf16 v[22:25], v[158:161], v[198:201], v[22:25]
	v_mfma_f32_16x16x32_bf16 v[14:17], v[146:149], v[206:209], v[14:17]
	v_mfma_f32_16x16x32_bf16 v[6:9], v[158:161], v[206:209], v[6:9]
	v_mfma_f32_16x16x32_bf16 v[58:61], v[162:165], v[178:181], v[58:61]
	v_mfma_f32_16x16x32_bf16 v[50:53], v[170:173], v[178:181], v[50:53]
	v_mfma_f32_16x16x32_bf16 v[42:45], v[162:165], v[186:189], v[42:45]
	v_mfma_f32_16x16x32_bf16 v[34:37], v[170:173], v[186:189], v[34:37]
	v_mfma_f32_16x16x32_bf16 v[26:29], v[162:165], v[194:197], v[26:29]
	v_mfma_f32_16x16x32_bf16 v[18:21], v[170:173], v[194:197], v[18:21]
	v_mfma_f32_16x16x32_bf16 v[10:13], v[162:165], v[202:205], v[10:13]
	v_mfma_f32_16x16x32_bf16 v[2:5], v[170:173], v[202:205], v[2:5]
	v_mfma_f32_16x16x32_bf16 v[58:61], v[166:169], v[182:185], v[58:61]
	v_mfma_f32_16x16x32_bf16 v[50:53], v[174:177], v[182:185], v[50:53]
	v_mfma_f32_16x16x32_bf16 v[42:45], v[166:169], v[190:193], v[42:45]
	v_mfma_f32_16x16x32_bf16 v[34:37], v[174:177], v[190:193], v[34:37]
	v_mfma_f32_16x16x32_bf16 v[26:29], v[166:169], v[198:201], v[26:29]
	v_mfma_f32_16x16x32_bf16 v[18:21], v[174:177], v[198:201], v[18:21]
	v_mfma_f32_16x16x32_bf16 v[10:13], v[166:169], v[206:209], v[10:13]
	v_mfma_f32_16x16x32_bf16 v[2:5], v[174:177], v[206:209], v[2:5]
	s_setprio 0
	s_barrier
	s_add_i32 s85, s85, 2
	s_add_u32 s58, s58, 0x100
	s_addc_u32 s59, s59, 0
	s_add_u32 s73, s73, 0x100
	s_addc_u32 s84, s84, 0
	s_cmp_gt_u32 s85, 13
	s_cbranch_scc0 .LBB0_50
	s_and_b64 vcc, exec, s[48:49]
	s_cbranch_vccz .LBB0_53
	s_barrier

.LBB0_75:
	s_add_i32 s41, s28, 2
	s_add_u32 s8, s60, 0x80
	s_addc_u32 s9, s61, 0
	s_add_i32 s10, 0, 0x10000
	s_cmp_eq_u32 s84, s28
	s_cselect_b32 s29, s47, s9
	s_cselect_b32 s28, s46, s8
	s_cselect_b32 s9, s59, s40
	s_cselect_b32 s8, s58, s7
	s_add_i32 s11, 0, 0x14000
	v_add_u32_e32 v126, s10, v1
	v_add_u32_e32 v160, s11, v1
	ds_read_b128 v[98:101], v126
	ds_read_b128 v[102:105], v126 offset:1024
	ds_read_b128 v[122:125], v126 offset:2048
	ds_read_b128 v[126:129], v126 offset:3072
	ds_read_b128 v[144:147], v160
	ds_read_b128 v[148:151], v160 offset:1024
	ds_read_b128 v[156:159], v160 offset:2048
	ds_read_b128 v[160:163], v160 offset:3072
	v_lshl_add_u64 v[206:207], s[60:61], 0, v[194:195]
	s_add_i32 m0, s66, 0xc000
	ds_read_b128 v[164:167], v231
	ds_read_b128 v[168:171], v231 offset:1024
	ds_read_b128 v[172:175], v231 offset:2048
	ds_read_b128 v[176:179], v231 offset:3072
	ds_read_b128 v[180:183], v231 offset:4096
	ds_read_b128 v[184:187], v231 offset:5120
	ds_read_b128 v[198:201], v231 offset:6144
	ds_read_b128 v[202:205], v231 offset:7168
	global_load_lds_dwordx4 v[206:207], off
	v_lshl_add_u64 v[206:207], s[60:61], 0, v[196:197]
	s_add_i32 m0, s66, 0xe000
	s_nop 0
	global_load_lds_dwordx4 v[206:207], off
	s_waitcnt vmcnt(8)
	s_waitcnt lgkmcnt(0)
	s_barrier
	s_setprio 1
	v_mfma_f32_16x16x32_bf16 v[152:155], v[98:101], v[164:167], v[152:155]
	v_mfma_f32_16x16x32_bf16 v[140:143], v[122:125], v[164:167], v[140:143]
	v_mfma_f32_16x16x32_bf16 v[118:121], v[98:101], v[172:175], v[118:121]
	v_mfma_f32_16x16x32_bf16 v[114:117], v[122:125], v[172:175], v[114:117]
	v_mfma_f32_16x16x32_bf16 v[94:97], v[98:101], v[180:183], v[94:97]
	v_mfma_f32_16x16x32_bf16 v[90:93], v[122:125], v[180:183], v[90:93]
	v_mfma_f32_16x16x32_bf16 v[78:81], v[98:101], v[198:201], v[78:81]
	v_mfma_f32_16x16x32_bf16 v[74:77], v[122:125], v[198:201], v[74:77]
	v_mfma_f32_16x16x32_bf16 v[152:155], v[102:105], v[168:171], v[152:155]
	v_mfma_f32_16x16x32_bf16 v[140:143], v[126:129], v[168:171], v[140:143]
	v_mfma_f32_16x16x32_bf16 v[118:121], v[102:105], v[176:179], v[118:121]
	v_mfma_f32_16x16x32_bf16 v[114:117], v[126:129], v[176:179], v[114:117]
	v_mfma_f32_16x16x32_bf16 v[94:97], v[102:105], v[184:187], v[94:97]
	v_mfma_f32_16x16x32_bf16 v[90:93], v[126:129], v[184:187], v[90:93]
	v_mfma_f32_16x16x32_bf16 v[78:81], v[102:105], v[202:205], v[78:81]
	v_mfma_f32_16x16x32_bf16 v[74:77], v[126:129], v[202:205], v[74:77]
	v_mfma_f32_16x16x32_bf16 v[136:139], v[144:147], v[164:167], v[136:139]
	v_mfma_f32_16x16x32_bf16 v[132:135], v[156:159], v[164:167], v[132:135]
	v_mfma_f32_16x16x32_bf16 v[110:113], v[144:147], v[172:175], v[110:113]
	v_mfma_f32_16x16x32_bf16 v[106:109], v[156:159], v[172:175], v[106:109]
	v_mfma_f32_16x16x32_bf16 v[86:89], v[144:147], v[180:183], v[86:89]
	v_mfma_f32_16x16x32_bf16 v[82:85], v[156:159], v[180:183], v[82:85]
	v_mfma_f32_16x16x32_bf16 v[70:73], v[144:147], v[198:201], v[70:73]
	v_mfma_f32_16x16x32_bf16 v[66:69], v[156:159], v[198:201], v[66:69]
	v_mfma_f32_16x16x32_bf16 v[136:139], v[148:151], v[168:171], v[136:139]
	v_mfma_f32_16x16x32_bf16 v[132:135], v[160:163], v[168:171], v[132:135]
	v_mfma_f32_16x16x32_bf16 v[110:113], v[148:151], v[176:179], v[110:113]
	v_mfma_f32_16x16x32_bf16 v[106:109], v[160:163], v[176:179], v[106:109]
	v_mfma_f32_16x16x32_bf16 v[86:89], v[148:151], v[184:187], v[86:89]
	v_mfma_f32_16x16x32_bf16 v[82:85], v[160:163], v[184:187], v[82:85]
	v_mfma_f32_16x16x32_bf16 v[70:73], v[148:151], v[202:205], v[70:73]
	v_mfma_f32_16x16x32_bf16 v[66:69], v[160:163], v[202:205], v[66:69]
	s_setprio 0
	s_barrier
	s_add_i32 s10, s10, s64
	v_lshl_add_u64 v[206:207], s[8:9], 0, v[130:131]
	s_mov_b32 m0, s10
	ds_read_b128 v[164:167], v231 offset:16384
	ds_read_b128 v[168:171], v231 offset:17408
	ds_read_b128 v[172:175], v231 offset:18432
	ds_read_b128 v[176:179], v231 offset:19456
	ds_read_b128 v[180:183], v231 offset:20480
	ds_read_b128 v[184:187], v231 offset:21504
	ds_read_b128 v[198:201], v231 offset:22528
	ds_read_b128 v[202:205], v231 offset:23552
	global_load_lds_dwordx4 v[206:207], off
	s_add_i32 m0, s10, 0x2000
	v_lshl_add_u64 v[208:209], s[8:9], 0, v[188:189]
	s_add_u32 s8, s8, s48
	s_addc_u32 s9, s9, 0
	s_add_i32 s10, s11, s64
	global_load_lds_dwordx4 v[208:209], off
	v_lshl_add_u64 v[210:211], s[8:9], 0, v[130:131]
	s_mov_b32 m0, s10
	v_lshl_add_u64 v[212:213], s[8:9], 0, v[188:189]
	global_load_lds_dwordx4 v[210:211], off
	s_add_i32 m0, s10, 0x2000
	v_lshl_add_u64 v[214:215], s[28:29], 0, v[192:193]
	global_load_lds_dwordx4 v[212:213], off
	s_mov_b32 m0, s66
	v_lshl_add_u64 v[216:217], s[28:29], 0, v[190:191]
	global_load_lds_dwordx4 v[214:215], off
	s_mov_b32 m0, s67
	s_nop 0
	global_load_lds_dwordx4 v[216:217], off
	s_waitcnt vmcnt(8)
	s_waitcnt lgkmcnt(0)
	s_barrier
	s_setprio 1
	v_mfma_f32_16x16x32_bf16 v[62:65], v[98:101], v[164:167], v[62:65]
	v_mfma_f32_16x16x32_bf16 v[58:61], v[122:125], v[164:167], v[58:61]
	v_mfma_f32_16x16x32_bf16 v[46:49], v[98:101], v[172:175], v[46:49]
	v_mfma_f32_16x16x32_bf16 v[42:45], v[122:125], v[172:175], v[42:45]
	v_mfma_f32_16x16x32_bf16 v[30:33], v[98:101], v[180:183], v[30:33]
	v_mfma_f32_16x16x32_bf16 v[26:29], v[122:125], v[180:183], v[26:29]
	v_mfma_f32_16x16x32_bf16 v[14:17], v[98:101], v[198:201], v[14:17]
	v_mfma_f32_16x16x32_bf16 v[10:13], v[122:125], v[198:201], v[10:13]
	v_mfma_f32_16x16x32_bf16 v[62:65], v[102:105], v[168:171], v[62:65]
	v_mfma_f32_16x16x32_bf16 v[58:61], v[126:129], v[168:171], v[58:61]
	v_mfma_f32_16x16x32_bf16 v[46:49], v[102:105], v[176:179], v[46:49]
	v_mfma_f32_16x16x32_bf16 v[42:45], v[126:129], v[176:179], v[42:45]
	v_mfma_f32_16x16x32_bf16 v[30:33], v[102:105], v[184:187], v[30:33]
	v_mfma_f32_16x16x32_bf16 v[26:29], v[126:129], v[184:187], v[26:29]
	v_mfma_f32_16x16x32_bf16 v[14:17], v[102:105], v[202:205], v[14:17]
	v_mfma_f32_16x16x32_bf16 v[10:13], v[126:129], v[202:205], v[10:13]
	v_mfma_f32_16x16x32_bf16 v[54:57], v[144:147], v[164:167], v[54:57]
	v_mfma_f32_16x16x32_bf16 v[50:53], v[156:159], v[164:167], v[50:53]
	v_mfma_f32_16x16x32_bf16 v[38:41], v[144:147], v[172:175], v[38:41]
	v_mfma_f32_16x16x32_bf16 v[34:37], v[156:159], v[172:175], v[34:37]
	v_mfma_f32_16x16x32_bf16 v[22:25], v[144:147], v[180:183], v[22:25]
	v_mfma_f32_16x16x32_bf16 v[18:21], v[156:159], v[180:183], v[18:21]
	v_mfma_f32_16x16x32_bf16 v[6:9], v[144:147], v[198:201], v[6:9]
	v_mfma_f32_16x16x32_bf16 v[2:5], v[156:159], v[198:201], v[2:5]
	v_mfma_f32_16x16x32_bf16 v[54:57], v[148:151], v[168:171], v[54:57]
	v_mfma_f32_16x16x32_bf16 v[50:53], v[160:163], v[168:171], v[50:53]
	v_mfma_f32_16x16x32_bf16 v[38:41], v[148:151], v[176:179], v[38:41]
	v_mfma_f32_16x16x32_bf16 v[34:37], v[160:163], v[176:179], v[34:37]
	v_mfma_f32_16x16x32_bf16 v[22:25], v[148:151], v[184:187], v[22:25]
	v_mfma_f32_16x16x32_bf16 v[18:21], v[160:163], v[184:187], v[18:21]
	v_mfma_f32_16x16x32_bf16 v[6:9], v[148:151], v[202:205], v[6:9]
	v_mfma_f32_16x16x32_bf16 v[2:5], v[160:163], v[202:205], v[2:5]
	s_setprio 0
	s_barrier
	s_add_i32 s10, 0, 0x18000
	s_add_i32 s11, 0, 0x1c000
	v_add_u32_e32 v126, s10, v1
	v_add_u32_e32 v160, s11, v1
	ds_read_b128 v[98:101], v126
	ds_read_b128 v[102:105], v126 offset:1024
	ds_read_b128 v[122:125], v126 offset:2048
	ds_read_b128 v[126:129], v126 offset:3072
	ds_read_b128 v[144:147], v160
	ds_read_b128 v[148:151], v160 offset:1024
	ds_read_b128 v[156:159], v160 offset:2048
	ds_read_b128 v[160:163], v160 offset:3072
	s_add_u32 s8, s28, s48
	s_addc_u32 s9, s29, 0
	s_mov_b32 m0, s68
	v_lshl_add_u64 v[218:219], s[8:9], 0, v[192:193]
	ds_read_b128 v[164:167], v231 offset:32768
	ds_read_b128 v[168:171], v231 offset:33792
	ds_read_b128 v[172:175], v231 offset:34816
	ds_read_b128 v[176:179], v231 offset:35840
	ds_read_b128 v[180:183], v231 offset:36864
	ds_read_b128 v[184:187], v231 offset:37888
	ds_read_b128 v[198:201], v231 offset:38912
	ds_read_b128 v[202:205], v231 offset:39936
	global_load_lds_dwordx4 v[218:219], off
	v_lshl_add_u64 v[218:219], s[8:9], 0, v[190:191]
	s_mov_b32 m0, s69
	s_nop 0
	global_load_lds_dwordx4 v[218:219], off
	s_waitcnt vmcnt(8)
	s_waitcnt lgkmcnt(0)
	s_barrier
	s_setprio 1
	v_mfma_f32_16x16x32_bf16 v[152:155], v[98:101], v[164:167], v[152:155]
	v_mfma_f32_16x16x32_bf16 v[140:143], v[122:125], v[164:167], v[140:143]
	v_mfma_f32_16x16x32_bf16 v[118:121], v[98:101], v[172:175], v[118:121]
	v_mfma_f32_16x16x32_bf16 v[114:117], v[122:125], v[172:175], v[114:117]
	v_mfma_f32_16x16x32_bf16 v[94:97], v[98:101], v[180:183], v[94:97]
	v_mfma_f32_16x16x32_bf16 v[90:93], v[122:125], v[180:183], v[90:93]
	v_mfma_f32_16x16x32_bf16 v[78:81], v[98:101], v[198:201], v[78:81]
	v_mfma_f32_16x16x32_bf16 v[74:77], v[122:125], v[198:201], v[74:77]
	v_mfma_f32_16x16x32_bf16 v[152:155], v[102:105], v[168:171], v[152:155]
	v_mfma_f32_16x16x32_bf16 v[140:143], v[126:129], v[168:171], v[140:143]
	v_mfma_f32_16x16x32_bf16 v[118:121], v[102:105], v[176:179], v[118:121]
	v_mfma_f32_16x16x32_bf16 v[114:117], v[126:129], v[176:179], v[114:117]
	v_mfma_f32_16x16x32_bf16 v[94:97], v[102:105], v[184:187], v[94:97]
	v_mfma_f32_16x16x32_bf16 v[90:93], v[126:129], v[184:187], v[90:93]
	v_mfma_f32_16x16x32_bf16 v[78:81], v[102:105], v[202:205], v[78:81]
	v_mfma_f32_16x16x32_bf16 v[74:77], v[126:129], v[202:205], v[74:77]
	v_mfma_f32_16x16x32_bf16 v[136:139], v[144:147], v[164:167], v[136:139]
	v_mfma_f32_16x16x32_bf16 v[132:135], v[156:159], v[164:167], v[132:135]
	v_mfma_f32_16x16x32_bf16 v[110:113], v[144:147], v[172:175], v[110:113]
	v_mfma_f32_16x16x32_bf16 v[106:109], v[156:159], v[172:175], v[106:109]
	v_mfma_f32_16x16x32_bf16 v[86:89], v[144:147], v[180:183], v[86:89]
	v_mfma_f32_16x16x32_bf16 v[82:85], v[156:159], v[180:183], v[82:85]
	v_mfma_f32_16x16x32_bf16 v[70:73], v[144:147], v[198:201], v[70:73]
	v_mfma_f32_16x16x32_bf16 v[66:69], v[156:159], v[198:201], v[66:69]
	v_mfma_f32_16x16x32_bf16 v[136:139], v[148:151], v[168:171], v[136:139]
	v_mfma_f32_16x16x32_bf16 v[132:135], v[160:163], v[168:171], v[132:135]
	v_mfma_f32_16x16x32_bf16 v[110:113], v[148:151], v[176:179], v[110:113]
	v_mfma_f32_16x16x32_bf16 v[106:109], v[160:163], v[176:179], v[106:109]
	v_mfma_f32_16x16x32_bf16 v[86:89], v[148:151], v[184:187], v[86:89]
	v_mfma_f32_16x16x32_bf16 v[82:85], v[160:163], v[184:187], v[82:85]
	v_mfma_f32_16x16x32_bf16 v[70:73], v[148:151], v[202:205], v[70:73]
	v_mfma_f32_16x16x32_bf16 v[66:69], v[160:163], v[202:205], v[66:69]
	s_setprio 0
	s_barrier
	s_add_i32 s8, s10, s64
	v_lshl_add_u64 v[206:207], v[206:207], 0, s[82:83]
	s_mov_b32 m0, s8
	ds_read_b128 v[164:167], v231 offset:49152
	ds_read_b128 v[168:171], v231 offset:50176
	ds_read_b128 v[172:175], v231 offset:51200
	ds_read_b128 v[176:179], v231 offset:52224
	ds_read_b128 v[180:183], v231 offset:53248
	ds_read_b128 v[184:187], v231 offset:54272
	ds_read_b128 v[198:201], v231 offset:55296
	ds_read_b128 v[202:205], v231 offset:56320
	global_load_lds_dwordx4 v[206:207], off
	v_lshl_add_u64 v[206:207], v[208:209], 0, s[82:83]
	s_add_i32 m0, s8, 0x2000
	s_add_i32 s8, s11, s64
	global_load_lds_dwordx4 v[206:207], off
	v_lshl_add_u64 v[206:207], v[210:211], 0, s[82:83]
	s_mov_b32 m0, s8
	s_nop 0
	global_load_lds_dwordx4 v[206:207], off
	v_lshl_add_u64 v[206:207], v[212:213], 0, s[82:83]
	s_add_i32 m0, s8, 0x2000
	s_nop 0
	global_load_lds_dwordx4 v[206:207], off
	v_lshl_add_u64 v[206:207], v[214:215], 0, s[82:83]
	s_mov_b32 m0, s85
	s_nop 0
	global_load_lds_dwordx4 v[206:207], off
	v_lshl_add_u64 v[206:207], v[216:217], 0, s[82:83]
	s_mov_b32 m0, s88
	s_nop 0
	global_load_lds_dwordx4 v[206:207], off
	s_waitcnt vmcnt(8)
	s_waitcnt lgkmcnt(0)
	s_barrier
	s_setprio 1
	v_mfma_f32_16x16x32_bf16 v[62:65], v[98:101], v[164:167], v[62:65]
	v_mfma_f32_16x16x32_bf16 v[58:61], v[122:125], v[164:167], v[58:61]
	v_mfma_f32_16x16x32_bf16 v[46:49], v[98:101], v[172:175], v[46:49]
	v_mfma_f32_16x16x32_bf16 v[42:45], v[122:125], v[172:175], v[42:45]
	v_mfma_f32_16x16x32_bf16 v[30:33], v[98:101], v[180:183], v[30:33]
	v_mfma_f32_16x16x32_bf16 v[26:29], v[122:125], v[180:183], v[26:29]
	v_mfma_f32_16x16x32_bf16 v[14:17], v[98:101], v[198:201], v[14:17]
	v_mfma_f32_16x16x32_bf16 v[10:13], v[122:125], v[198:201], v[10:13]
	v_mfma_f32_16x16x32_bf16 v[62:65], v[102:105], v[168:171], v[62:65]
	v_mfma_f32_16x16x32_bf16 v[58:61], v[126:129], v[168:171], v[58:61]
	v_mfma_f32_16x16x32_bf16 v[46:49], v[102:105], v[176:179], v[46:49]
	v_mfma_f32_16x16x32_bf16 v[42:45], v[126:129], v[176:179], v[42:45]
	v_mfma_f32_16x16x32_bf16 v[30:33], v[102:105], v[184:187], v[30:33]
	v_mfma_f32_16x16x32_bf16 v[26:29], v[126:129], v[184:187], v[26:29]
	v_mfma_f32_16x16x32_bf16 v[14:17], v[102:105], v[202:205], v[14:17]
	v_mfma_f32_16x16x32_bf16 v[10:13], v[126:129], v[202:205], v[10:13]
	v_mfma_f32_16x16x32_bf16 v[54:57], v[144:147], v[164:167], v[54:57]
	v_mfma_f32_16x16x32_bf16 v[50:53], v[156:159], v[164:167], v[50:53]
	v_mfma_f32_16x16x32_bf16 v[38:41], v[144:147], v[172:175], v[38:41]
	v_mfma_f32_16x16x32_bf16 v[34:37], v[156:159], v[172:175], v[34:37]
	v_mfma_f32_16x16x32_bf16 v[22:25], v[144:147], v[180:183], v[22:25]
	v_mfma_f32_16x16x32_bf16 v[18:21], v[156:159], v[180:183], v[18:21]
	v_mfma_f32_16x16x32_bf16 v[6:9], v[144:147], v[198:201], v[6:9]
	v_mfma_f32_16x16x32_bf16 v[2:5], v[156:159], v[198:201], v[2:5]
	v_mfma_f32_16x16x32_bf16 v[54:57], v[148:151], v[168:171], v[54:57]
	v_mfma_f32_16x16x32_bf16 v[50:53], v[160:163], v[168:171], v[50:53]
	v_mfma_f32_16x16x32_bf16 v[38:41], v[148:151], v[176:179], v[38:41]
	v_mfma_f32_16x16x32_bf16 v[34:37], v[160:163], v[176:179], v[34:37]
	v_mfma_f32_16x16x32_bf16 v[22:25], v[148:151], v[184:187], v[22:25]
	v_mfma_f32_16x16x32_bf16 v[18:21], v[160:163], v[184:187], v[18:21]
	v_mfma_f32_16x16x32_bf16 v[6:9], v[148:151], v[202:205], v[6:9]
	v_mfma_f32_16x16x32_bf16 v[2:5], v[160:163], v[202:205], v[2:5]
	s_setprio 0
	s_barrier
	s_add_u32 s60, s60, 0x100
	s_addc_u32 s61, s61, 0
	s_add_u32 s7, s7, 0x100
	s_addc_u32 s40, s40, 0
	s_cmp_ge_u32 s41, s73
	s_mov_b32 s28, s41
	s_cbranch_scc0 .LBB0_75
	s_and_b64 vcc, exec, s[54:55]
	s_cbranch_vccz .LBB0_78
	s_barrier

.LBB0_497:
	s_add_u32 s8, s60, 0xfffc0080
	s_addc_u32 s9, s61, -1
	s_add_i32 s10, 0, 0x10000
	s_cmp_eq_u32 s84, 12
	s_cselect_b32 s41, s55, s9
	s_cselect_b32 s40, s72, s8
	s_cselect_b32 s29, s53, s77
	s_cselect_b32 s28, s73, s76
	s_add_i32 s11, 0, 0x14000
	v_add_u32_e32 v158, s10, v1
	v_add_u32_e32 v174, s11, v1
	ds_read_b128 v[146:149], v158
	ds_read_b128 v[150:153], v158 offset:1024
	ds_read_b128 v[154:157], v158 offset:2048
	ds_read_b128 v[158:161], v158 offset:3072
	ds_read_b128 v[162:165], v174
	ds_read_b128 v[166:169], v174 offset:1024
	ds_read_b128 v[170:173], v174 offset:2048
	ds_read_b128 v[174:177], v174 offset:3072
	v_lshl_add_u64 v[210:211], s[60:61], 0, v[138:139]
	s_add_i32 m0, s62, 0xc000
	ds_read_b128 v[178:181], v145
	ds_read_b128 v[182:185], v145 offset:1024
	ds_read_b128 v[186:189], v145 offset:2048
	ds_read_b128 v[190:193], v145 offset:3072
	ds_read_b128 v[194:197], v145 offset:4096
	ds_read_b128 v[198:201], v145 offset:5120
	ds_read_b128 v[202:205], v145 offset:6144
	ds_read_b128 v[206:209], v145 offset:7168
	global_load_lds_dwordx4 v[210:211], off
	v_lshl_add_u64 v[210:211], s[60:61], 0, v[140:141]
	s_add_i32 m0, s62, 0xe000
	s_nop 0
	global_load_lds_dwordx4 v[210:211], off
	s_waitcnt vmcnt(8)
	s_waitcnt lgkmcnt(0)
	s_barrier
	s_setprio 1
	v_mfma_f32_16x16x32_bf16 v[126:129], v[146:149], v[178:181], v[126:129]
	v_mfma_f32_16x16x32_bf16 v[122:125], v[154:157], v[178:181], v[122:125]
	v_mfma_f32_16x16x32_bf16 v[110:113], v[146:149], v[186:189], v[110:113]
	v_mfma_f32_16x16x32_bf16 v[106:109], v[154:157], v[186:189], v[106:109]
	v_mfma_f32_16x16x32_bf16 v[94:97], v[146:149], v[194:197], v[94:97]
	v_mfma_f32_16x16x32_bf16 v[90:93], v[154:157], v[194:197], v[90:93]
	v_mfma_f32_16x16x32_bf16 v[78:81], v[146:149], v[202:205], v[78:81]
	v_mfma_f32_16x16x32_bf16 v[74:77], v[154:157], v[202:205], v[74:77]
	v_mfma_f32_16x16x32_bf16 v[126:129], v[150:153], v[182:185], v[126:129]
	v_mfma_f32_16x16x32_bf16 v[122:125], v[158:161], v[182:185], v[122:125]
	v_mfma_f32_16x16x32_bf16 v[110:113], v[150:153], v[190:193], v[110:113]
	v_mfma_f32_16x16x32_bf16 v[106:109], v[158:161], v[190:193], v[106:109]
	v_mfma_f32_16x16x32_bf16 v[94:97], v[150:153], v[198:201], v[94:97]
	v_mfma_f32_16x16x32_bf16 v[90:93], v[158:161], v[198:201], v[90:93]
	v_mfma_f32_16x16x32_bf16 v[78:81], v[150:153], v[206:209], v[78:81]
	v_mfma_f32_16x16x32_bf16 v[74:77], v[158:161], v[206:209], v[74:77]
	v_mfma_f32_16x16x32_bf16 v[118:121], v[162:165], v[178:181], v[118:121]
	v_mfma_f32_16x16x32_bf16 v[114:117], v[170:173], v[178:181], v[114:117]
	v_mfma_f32_16x16x32_bf16 v[102:105], v[162:165], v[186:189], v[102:105]
	v_mfma_f32_16x16x32_bf16 v[98:101], v[170:173], v[186:189], v[98:101]
	v_mfma_f32_16x16x32_bf16 v[86:89], v[162:165], v[194:197], v[86:89]
	v_mfma_f32_16x16x32_bf16 v[82:85], v[170:173], v[194:197], v[82:85]
	v_mfma_f32_16x16x32_bf16 v[70:73], v[162:165], v[202:205], v[70:73]
	v_mfma_f32_16x16x32_bf16 v[66:69], v[170:173], v[202:205], v[66:69]
	v_mfma_f32_16x16x32_bf16 v[118:121], v[166:169], v[182:185], v[118:121]
	v_mfma_f32_16x16x32_bf16 v[114:117], v[174:177], v[182:185], v[114:117]
	v_mfma_f32_16x16x32_bf16 v[102:105], v[166:169], v[190:193], v[102:105]
	v_mfma_f32_16x16x32_bf16 v[98:101], v[174:177], v[190:193], v[98:101]
	v_mfma_f32_16x16x32_bf16 v[86:89], v[166:169], v[198:201], v[86:89]
	v_mfma_f32_16x16x32_bf16 v[82:85], v[174:177], v[198:201], v[82:85]
	v_mfma_f32_16x16x32_bf16 v[70:73], v[166:169], v[206:209], v[70:73]
	v_mfma_f32_16x16x32_bf16 v[66:69], v[174:177], v[206:209], v[66:69]
	s_setprio 0
	s_barrier
	s_add_i32 s8, s10, s34
	v_lshl_add_u64 v[210:211], s[28:29], 0, v[130:131]
	s_mov_b32 m0, s8
	ds_read_b128 v[178:181], v145 offset:16384
	ds_read_b128 v[182:185], v145 offset:17408
	ds_read_b128 v[186:189], v145 offset:18432
	ds_read_b128 v[190:193], v145 offset:19456
	ds_read_b128 v[194:197], v145 offset:20480
	ds_read_b128 v[198:201], v145 offset:21504
	ds_read_b128 v[202:205], v145 offset:22528
	ds_read_b128 v[206:209], v145 offset:23552
	global_load_lds_dwordx4 v[210:211], off
	s_add_i32 m0, s8, 0x2000
	s_add_u32 s8, s28, 0x40000
	v_lshl_add_u64 v[212:213], s[28:29], 0, v[132:133]
	s_addc_u32 s9, s29, 0
	s_add_i32 s10, s11, s34
	global_load_lds_dwordx4 v[212:213], off
	v_lshl_add_u64 v[214:215], s[8:9], 0, v[130:131]
	s_mov_b32 m0, s10
	v_lshl_add_u64 v[216:217], s[40:41], 0, v[134:135]
	global_load_lds_dwordx4 v[214:215], off
	v_lshl_add_u64 v[214:215], s[8:9], 0, v[132:133]
	s_add_i32 m0, s10, 0x2000
	s_nop 0
	global_load_lds_dwordx4 v[214:215], off
	v_lshl_add_u64 v[214:215], s[40:41], 0, v[136:137]
	s_mov_b32 m0, s62
	s_nop 0
	global_load_lds_dwordx4 v[214:215], off
	s_mov_b32 m0, s63
	s_nop 0
	global_load_lds_dwordx4 v[216:217], off
	s_waitcnt vmcnt(8)
	s_waitcnt lgkmcnt(0)
	s_barrier
	s_setprio 1
	v_mfma_f32_16x16x32_bf16 v[62:65], v[146:149], v[178:181], v[62:65]
	v_mfma_f32_16x16x32_bf16 v[58:61], v[154:157], v[178:181], v[58:61]
	v_mfma_f32_16x16x32_bf16 v[46:49], v[146:149], v[186:189], v[46:49]
	v_mfma_f32_16x16x32_bf16 v[42:45], v[154:157], v[186:189], v[42:45]
	v_mfma_f32_16x16x32_bf16 v[30:33], v[146:149], v[194:197], v[30:33]
	v_mfma_f32_16x16x32_bf16 v[26:29], v[154:157], v[194:197], v[26:29]
	v_mfma_f32_16x16x32_bf16 v[14:17], v[146:149], v[202:205], v[14:17]
	v_mfma_f32_16x16x32_bf16 v[10:13], v[154:157], v[202:205], v[10:13]
	v_mfma_f32_16x16x32_bf16 v[62:65], v[150:153], v[182:185], v[62:65]
	v_mfma_f32_16x16x32_bf16 v[58:61], v[158:161], v[182:185], v[58:61]
	v_mfma_f32_16x16x32_bf16 v[46:49], v[150:153], v[190:193], v[46:49]
	v_mfma_f32_16x16x32_bf16 v[42:45], v[158:161], v[190:193], v[42:45]
	v_mfma_f32_16x16x32_bf16 v[30:33], v[150:153], v[198:201], v[30:33]
	v_mfma_f32_16x16x32_bf16 v[26:29], v[158:161], v[198:201], v[26:29]
	v_mfma_f32_16x16x32_bf16 v[14:17], v[150:153], v[206:209], v[14:17]
	v_mfma_f32_16x16x32_bf16 v[10:13], v[158:161], v[206:209], v[10:13]
	v_mfma_f32_16x16x32_bf16 v[54:57], v[162:165], v[178:181], v[54:57]
	v_mfma_f32_16x16x32_bf16 v[50:53], v[170:173], v[178:181], v[50:53]
	v_mfma_f32_16x16x32_bf16 v[38:41], v[162:165], v[186:189], v[38:41]
	v_mfma_f32_16x16x32_bf16 v[34:37], v[170:173], v[186:189], v[34:37]
	v_mfma_f32_16x16x32_bf16 v[22:25], v[162:165], v[194:197], v[22:25]
	v_mfma_f32_16x16x32_bf16 v[18:21], v[170:173], v[194:197], v[18:21]
	v_mfma_f32_16x16x32_bf16 v[6:9], v[162:165], v[202:205], v[6:9]
	v_mfma_f32_16x16x32_bf16 v[2:5], v[170:173], v[202:205], v[2:5]
	v_mfma_f32_16x16x32_bf16 v[54:57], v[166:169], v[182:185], v[54:57]
	v_mfma_f32_16x16x32_bf16 v[50:53], v[174:177], v[182:185], v[50:53]
	v_mfma_f32_16x16x32_bf16 v[38:41], v[166:169], v[190:193], v[38:41]
	v_mfma_f32_16x16x32_bf16 v[34:37], v[174:177], v[190:193], v[34:37]
	v_mfma_f32_16x16x32_bf16 v[22:25], v[166:169], v[198:201], v[22:25]
	v_mfma_f32_16x16x32_bf16 v[18:21], v[174:177], v[198:201], v[18:21]
	v_mfma_f32_16x16x32_bf16 v[6:9], v[166:169], v[206:209], v[6:9]
	v_mfma_f32_16x16x32_bf16 v[2:5], v[174:177], v[206:209], v[2:5]
	s_setprio 0
	s_barrier
	s_add_i32 s10, 0, 0x18000
	s_add_i32 s11, 0, 0x1c000
	v_add_u32_e32 v158, s10, v1
	v_add_u32_e32 v174, s11, v1
	ds_read_b128 v[146:149], v158
	ds_read_b128 v[150:153], v158 offset:1024
	ds_read_b128 v[154:157], v158 offset:2048
	ds_read_b128 v[158:161], v158 offset:3072
	ds_read_b128 v[162:165], v174
	ds_read_b128 v[166:169], v174 offset:1024
	ds_read_b128 v[170:173], v174 offset:2048
	ds_read_b128 v[174:177], v174 offset:3072
	s_add_u32 s8, s40, 0x40000
	s_addc_u32 s9, s41, 0
	s_mov_b32 m0, s64
	v_lshl_add_u64 v[218:219], s[8:9], 0, v[136:137]
	ds_read_b128 v[178:181], v145 offset:32768
	ds_read_b128 v[182:185], v145 offset:33792
	ds_read_b128 v[186:189], v145 offset:34816
	ds_read_b128 v[190:193], v145 offset:35840
	ds_read_b128 v[194:197], v145 offset:36864
	ds_read_b128 v[198:201], v145 offset:37888
	ds_read_b128 v[202:205], v145 offset:38912
	ds_read_b128 v[206:209], v145 offset:39936
	global_load_lds_dwordx4 v[218:219], off
	v_lshl_add_u64 v[218:219], s[8:9], 0, v[134:135]
	s_mov_b32 m0, s65
	s_nop 0
	global_load_lds_dwordx4 v[218:219], off
	s_waitcnt vmcnt(8)
	s_waitcnt lgkmcnt(0)
	s_barrier
	s_setprio 1
	v_mfma_f32_16x16x32_bf16 v[126:129], v[146:149], v[178:181], v[126:129]
	v_mfma_f32_16x16x32_bf16 v[122:125], v[154:157], v[178:181], v[122:125]
	v_mfma_f32_16x16x32_bf16 v[110:113], v[146:149], v[186:189], v[110:113]
	v_mfma_f32_16x16x32_bf16 v[106:109], v[154:157], v[186:189], v[106:109]
	v_mfma_f32_16x16x32_bf16 v[94:97], v[146:149], v[194:197], v[94:97]
	v_mfma_f32_16x16x32_bf16 v[90:93], v[154:157], v[194:197], v[90:93]
	v_mfma_f32_16x16x32_bf16 v[78:81], v[146:149], v[202:205], v[78:81]
	v_mfma_f32_16x16x32_bf16 v[74:77], v[154:157], v[202:205], v[74:77]
	v_mfma_f32_16x16x32_bf16 v[126:129], v[150:153], v[182:185], v[126:129]
	v_mfma_f32_16x16x32_bf16 v[122:125], v[158:161], v[182:185], v[122:125]
	v_mfma_f32_16x16x32_bf16 v[110:113], v[150:153], v[190:193], v[110:113]
	v_mfma_f32_16x16x32_bf16 v[106:109], v[158:161], v[190:193], v[106:109]
	v_mfma_f32_16x16x32_bf16 v[94:97], v[150:153], v[198:201], v[94:97]
	v_mfma_f32_16x16x32_bf16 v[90:93], v[158:161], v[198:201], v[90:93]
	v_mfma_f32_16x16x32_bf16 v[78:81], v[150:153], v[206:209], v[78:81]
	v_mfma_f32_16x16x32_bf16 v[74:77], v[158:161], v[206:209], v[74:77]
	v_mfma_f32_16x16x32_bf16 v[118:121], v[162:165], v[178:181], v[118:121]
	v_mfma_f32_16x16x32_bf16 v[114:117], v[170:173], v[178:181], v[114:117]
	v_mfma_f32_16x16x32_bf16 v[102:105], v[162:165], v[186:189], v[102:105]
	v_mfma_f32_16x16x32_bf16 v[98:101], v[170:173], v[186:189], v[98:101]
	v_mfma_f32_16x16x32_bf16 v[86:89], v[162:165], v[194:197], v[86:89]
	v_mfma_f32_16x16x32_bf16 v[82:85], v[170:173], v[194:197], v[82:85]
	v_mfma_f32_16x16x32_bf16 v[70:73], v[162:165], v[202:205], v[70:73]
	v_mfma_f32_16x16x32_bf16 v[66:69], v[170:173], v[202:205], v[66:69]
	v_mfma_f32_16x16x32_bf16 v[118:121], v[166:169], v[182:185], v[118:121]
	v_mfma_f32_16x16x32_bf16 v[114:117], v[174:177], v[182:185], v[114:117]
	v_mfma_f32_16x16x32_bf16 v[102:105], v[166:169], v[190:193], v[102:105]
	v_mfma_f32_16x16x32_bf16 v[98:101], v[174:177], v[190:193], v[98:101]
	v_mfma_f32_16x16x32_bf16 v[86:89], v[166:169], v[198:201], v[86:89]
	v_mfma_f32_16x16x32_bf16 v[82:85], v[174:177], v[198:201], v[82:85]
	v_mfma_f32_16x16x32_bf16 v[70:73], v[166:169], v[206:209], v[70:73]
	v_mfma_f32_16x16x32_bf16 v[66:69], v[174:177], v[206:209], v[66:69]
	s_setprio 0
	s_barrier
	s_add_i32 s8, s10, s34
	v_lshl_add_u64 v[210:211], v[210:211], 0, s[82:83]
	s_mov_b32 m0, s8
	ds_read_b128 v[178:181], v145 offset:49152
	ds_read_b128 v[182:185], v145 offset:50176
	ds_read_b128 v[186:189], v145 offset:51200
	ds_read_b128 v[190:193], v145 offset:52224
	ds_read_b128 v[194:197], v145 offset:53248
	ds_read_b128 v[198:201], v145 offset:54272
	ds_read_b128 v[202:205], v145 offset:55296
	ds_read_b128 v[206:209], v145 offset:56320
	global_load_lds_dwordx4 v[210:211], off
	s_add_i32 m0, s8, 0x2000
	s_add_u32 s8, s28, 0x40080
	v_lshl_add_u64 v[210:211], v[212:213], 0, s[82:83]
	s_addc_u32 s9, s29, 0
	s_add_i32 s10, s11, s34
	global_load_lds_dwordx4 v[210:211], off
	v_lshl_add_u64 v[210:211], s[8:9], 0, v[130:131]
	s_mov_b32 m0, s10
	s_nop 0
	global_load_lds_dwordx4 v[210:211], off
	v_lshl_add_u64 v[210:211], s[8:9], 0, v[132:133]
	s_add_i32 m0, s10, 0x2000
	s_nop 0
	global_load_lds_dwordx4 v[210:211], off
	v_lshl_add_u64 v[210:211], v[214:215], 0, s[82:83]
	s_mov_b32 m0, s66
	s_nop 0
	global_load_lds_dwordx4 v[210:211], off
	v_lshl_add_u64 v[210:211], v[216:217], 0, s[82:83]
	s_mov_b32 m0, s67
	s_nop 0
	global_load_lds_dwordx4 v[210:211], off
	s_waitcnt vmcnt(8)
	s_waitcnt lgkmcnt(0)
	s_barrier
	s_setprio 1
	v_mfma_f32_16x16x32_bf16 v[62:65], v[146:149], v[178:181], v[62:65]
	v_mfma_f32_16x16x32_bf16 v[58:61], v[154:157], v[178:181], v[58:61]
	v_mfma_f32_16x16x32_bf16 v[46:49], v[146:149], v[186:189], v[46:49]
	v_mfma_f32_16x16x32_bf16 v[42:45], v[154:157], v[186:189], v[42:45]
	v_mfma_f32_16x16x32_bf16 v[30:33], v[146:149], v[194:197], v[30:33]
	v_mfma_f32_16x16x32_bf16 v[26:29], v[154:157], v[194:197], v[26:29]
	v_mfma_f32_16x16x32_bf16 v[14:17], v[146:149], v[202:205], v[14:17]
	v_mfma_f32_16x16x32_bf16 v[10:13], v[154:157], v[202:205], v[10:13]
	v_mfma_f32_16x16x32_bf16 v[62:65], v[150:153], v[182:185], v[62:65]
	v_mfma_f32_16x16x32_bf16 v[58:61], v[158:161], v[182:185], v[58:61]
	v_mfma_f32_16x16x32_bf16 v[46:49], v[150:153], v[190:193], v[46:49]
	v_mfma_f32_16x16x32_bf16 v[42:45], v[158:161], v[190:193], v[42:45]
	v_mfma_f32_16x16x32_bf16 v[30:33], v[150:153], v[198:201], v[30:33]
	v_mfma_f32_16x16x32_bf16 v[26:29], v[158:161], v[198:201], v[26:29]
	v_mfma_f32_16x16x32_bf16 v[14:17], v[150:153], v[206:209], v[14:17]
	v_mfma_f32_16x16x32_bf16 v[10:13], v[158:161], v[206:209], v[10:13]
	v_mfma_f32_16x16x32_bf16 v[54:57], v[162:165], v[178:181], v[54:57]
	v_mfma_f32_16x16x32_bf16 v[50:53], v[170:173], v[178:181], v[50:53]
	v_mfma_f32_16x16x32_bf16 v[38:41], v[162:165], v[186:189], v[38:41]
	v_mfma_f32_16x16x32_bf16 v[34:37], v[170:173], v[186:189], v[34:37]
	v_mfma_f32_16x16x32_bf16 v[22:25], v[162:165], v[194:197], v[22:25]
	v_mfma_f32_16x16x32_bf16 v[18:21], v[170:173], v[194:197], v[18:21]
	v_mfma_f32_16x16x32_bf16 v[6:9], v[162:165], v[202:205], v[6:9]
	v_mfma_f32_16x16x32_bf16 v[2:5], v[170:173], v[202:205], v[2:5]
	v_mfma_f32_16x16x32_bf16 v[54:57], v[166:169], v[182:185], v[54:57]
	v_mfma_f32_16x16x32_bf16 v[50:53], v[174:177], v[182:185], v[50:53]
	v_mfma_f32_16x16x32_bf16 v[38:41], v[166:169], v[190:193], v[38:41]
	v_mfma_f32_16x16x32_bf16 v[34:37], v[174:177], v[190:193], v[34:37]
	v_mfma_f32_16x16x32_bf16 v[22:25], v[166:169], v[198:201], v[22:25]
	v_mfma_f32_16x16x32_bf16 v[18:21], v[174:177], v[198:201], v[18:21]
	v_mfma_f32_16x16x32_bf16 v[6:9], v[166:169], v[206:209], v[6:9]
	v_mfma_f32_16x16x32_bf16 v[2:5], v[174:177], v[206:209], v[2:5]
	s_setprio 0
	s_barrier
	s_add_i32 s84, s84, 2
	s_add_u32 s60, s60, 0x100
	s_addc_u32 s61, s61, 0
	s_add_u32 s76, s76, 0x100
	s_addc_u32 s77, s77, 0
	s_cmp_gt_u32 s84, 13
	s_cbranch_scc0 .LBB0_497
	s_and_b64 vcc, exec, s[50:51]
	s_cbranch_vccz .LBB0_500
	s_barrier
